# plus MLA attention QK interleaved MFMA chains with 4 rotating fragment buffers (no LDS double-buffer)
# speedup vs baseline: 1.0047x; 1.0047x over previous
; #define MFMA(a, b, c) __builtin_amdgcn_mfma_f32_32x32x16_bf16((a), (b), (c), 0, 0, 0)
; template <int DQ, bool MASK>
; DI void attn_phase(const Params& p, unsigned char* smem, float cexp) {
;     ...
;       __syncthreads();
;       {
;         constexpr int CPR = DQ / 8;
; #pragma unroll
;         for (int i = 0; i < DQ / 32; ++i) {
;           int c = tid + 256 * i;
;           int row = c / CPR, cc = c % CPR;
;           uint4 v = *(const uint4*)(Kb + ((size_t)bh * 2048 + kt * 64 + row) * DQ + cc * 8);
;           *(uint4*)(Ks + row * KST + cc * 8) = v;
;         }
; #pragma unroll
;         for (int i = 0; i < 4; ++i) {
;           int c = tid + 256 * i;
;           int d = c >> 3, cc = c & 7;
;           uint4 v = *(const uint4*)(Vt + (((size_t)bh * 32 + kt) * 128 + d) * 64 + cc * 8);
;           uint2* dp = (uint2*)(Vs + d * VST + cc * 8);
;           dp[0] = make_uint2(v.x, v.y);
;           dp[1] = make_uint2(v.z, v.w);
;         }
;       }
;       __syncthreads();
;       if (kt < my_nt) {
;         f32x16 sa[2];
; #pragma unroll
;         for (int u = 0; u < 2; ++u) {
; #pragma unroll
;           for (int i = 0; i < 16; ++i) sa[u][i] = 0.f;
; #pragma unroll
;           for (int s = 0; s < DQ / 16; ++s) {
;             bf16x8 a = *(const bf16x8*)(Ks + (32 * u + r) * KST + 16 * s + 8 * g);
;             sa[u] = MFMA(a, qf[s], sa[u]);
;           }
;         }
;         if (MASK) {
;           u64 mw = mask[tok * 32 + kt] >> (4 * g);
;           const u32 mlo = (u32)mw, mhi = (u32)(mw >> 32);
; #pragma unroll
;           for (int i = 0; i < 16; ++i) {
;             const u32 bit = 1u << ((i & 3) + 8 * (i >> 2));
;             if (!(mlo & bit)) sa[0][i] = -INFINITY;
;             if (!(mhi & bit)) sa[1][i] = -INFINITY;
;           }
;         }
;         float mx = -INFINITY;
; #pragma unroll
;         for (int u = 0; u < 2; ++u)
; #pragma unroll
;           for (int i = 0; i < 16; ++i) mx = fmaxf(mx, sa[u][i]);
;         mx = fmaxf(mx, __shfl_xor(mx, 32));
.LBB0_422:
	v_lshl_add_u64 v[2:3], s[22:23], 0, v[206:207]
	v_lshl_add_u64 v[6:7], s[22:23], 0, v[208:209]
	v_lshl_add_u64 v[10:11], s[22:23], 0, v[210:211]
	v_lshl_add_u64 v[14:15], s[22:23], 0, v[212:213]
	s_waitcnt vmcnt(63) expcnt(7) lgkmcnt(15)
	s_barrier
	global_load_dwordx4 v[2:5], v[2:3], off
	s_nop 0
	global_load_dwordx4 v[6:9], v[6:7], off
	s_nop 0
	global_load_dwordx4 v[10:13], v[10:11], off
	s_nop 0
	global_load_dwordx4 v[80:83], v[14:15], off
	v_lshl_add_u64 v[14:15], s[22:23], 0, v[214:215]
	v_lshl_add_u64 v[88:89], s[22:23], 0, v[216:217]
	global_load_dwordx4 v[84:87], v[14:15], off
	s_nop 0
	global_load_dwordx4 v[88:91], v[88:89], off
	v_lshl_add_u64 v[14:15], s[22:23], 0, v[204:205]
	v_add_co_u32_e32 v14, vcc, s62, v14
	v_lshl_add_u64 v[92:93], s[22:23], 0, v[202:203]
	s_nop 0
	v_addc_co_u32_e32 v15, vcc, 0, v15, vcc
	v_add_co_u32_e32 v96, vcc, s62, v92
	v_lshl_add_u64 v[100:101], s[22:23], 0, v[198:199]
	s_nop 0
	v_addc_co_u32_e32 v97, vcc, 0, v93, vcc
	global_load_dwordx4 v[92:95], v[14:15], off
	s_nop 0
	global_load_dwordx4 v[96:99], v[96:97], off
	v_lshl_add_u64 v[14:15], s[22:23], 0, v[200:201]
	v_add_co_u32_e32 v14, vcc, s62, v14
	s_nop 1
	v_addc_co_u32_e32 v15, vcc, 0, v15, vcc
	v_add_co_u32_e32 v104, vcc, 0xe000000, v100
	s_nop 1
	v_addc_co_u32_e32 v105, vcc, 0, v101, vcc
	global_load_dwordx4 v[100:103], v[14:15], off
	s_nop 0
	global_load_dwordx4 v[104:107], v[104:105], off
	v_cmp_lt_i32_e32 vcc, s54, v197
	s_waitcnt vmcnt(9)
	ds_write_b128 v229, v[2:5]
	s_waitcnt vmcnt(8)
	ds_write_b128 v230, v[6:9]
	s_waitcnt vmcnt(7)
	ds_write_b128 v231, v[10:13]
	s_waitcnt vmcnt(6)
	ds_write_b128 v232, v[80:83]
	s_waitcnt vmcnt(5)
	ds_write_b128 v233, v[84:87]
	s_waitcnt vmcnt(4)
	ds_write_b128 v234, v[88:91]
	s_waitcnt vmcnt(3)
	ds_write2_b64 v235, v[92:93], v[94:95] offset1:1
	s_waitcnt vmcnt(2)
	ds_write2_b64 v236, v[96:97], v[98:99] offset1:1
	s_waitcnt vmcnt(1)
	ds_write2_b64 v237, v[100:101], v[102:103] offset1:1
	s_waitcnt vmcnt(0)
	ds_write2_b64 v238, v[104:105], v[106:107] offset1:1
	s_waitcnt lgkmcnt(0)
	s_barrier
	s_and_saveexec_b64 s[12:13], vcc
	s_cbranch_execz .LBB0_421
	ds_read_b128 v[2:5], v239
	ds_read_b128 v[6:9], v239 offset:12800
	ds_read_b128 v[244:247], v239 offset:32
	ds_read_b128 v[248:251], v239 offset:12832
	s_waitcnt lgkmcnt(3)
	v_mfma_f32_32x32x16_bf16 v[96:111], v[2:5], v[112:115], 0
	ds_read_b128 v[2:5], v239 offset:64
	s_waitcnt lgkmcnt(3)
	v_mfma_f32_32x32x16_bf16 v[80:95], v[6:9], v[112:115], 0
	ds_read_b128 v[6:9], v239 offset:12864
	s_waitcnt lgkmcnt(3)
	v_mfma_f32_32x32x16_bf16 v[96:111], v[244:247], v[116:119], v[96:111]
	ds_read_b128 v[244:247], v239 offset:96
	s_waitcnt lgkmcnt(3)
	v_mfma_f32_32x32x16_bf16 v[80:95], v[248:251], v[116:119], v[80:95]
	ds_read_b128 v[248:251], v239 offset:12896
	s_waitcnt lgkmcnt(3)
	v_mfma_f32_32x32x16_bf16 v[96:111], v[2:5], v[120:123], v[96:111]
	ds_read_b128 v[2:5], v239 offset:128
	s_waitcnt lgkmcnt(3)
	v_mfma_f32_32x32x16_bf16 v[80:95], v[6:9], v[120:123], v[80:95]
	ds_read_b128 v[6:9], v239 offset:12928
	s_waitcnt lgkmcnt(3)
	v_mfma_f32_32x32x16_bf16 v[96:111], v[244:247], v[124:127], v[96:111]
	ds_read_b128 v[244:247], v239 offset:160
	s_waitcnt lgkmcnt(3)
	v_mfma_f32_32x32x16_bf16 v[80:95], v[248:251], v[124:127], v[80:95]
	ds_read_b128 v[248:251], v239 offset:12960
	s_waitcnt lgkmcnt(3)
	v_mfma_f32_32x32x16_bf16 v[96:111], v[2:5], v[128:131], v[96:111]
	ds_read_b128 v[2:5], v239 offset:192
	s_waitcnt lgkmcnt(3)
	v_mfma_f32_32x32x16_bf16 v[80:95], v[6:9], v[128:131], v[80:95]
	ds_read_b128 v[6:9], v239 offset:12992
	s_waitcnt lgkmcnt(3)
	v_mfma_f32_32x32x16_bf16 v[96:111], v[244:247], v[132:135], v[96:111]
	ds_read_b128 v[244:247], v239 offset:224
	s_waitcnt lgkmcnt(3)
	v_mfma_f32_32x32x16_bf16 v[80:95], v[248:251], v[132:135], v[80:95]
	ds_read_b128 v[248:251], v239 offset:13024
	s_waitcnt lgkmcnt(3)
	v_mfma_f32_32x32x16_bf16 v[96:111], v[2:5], v[136:139], v[96:111]
	ds_read_b128 v[2:5], v239 offset:256
	s_waitcnt lgkmcnt(3)
	v_mfma_f32_32x32x16_bf16 v[80:95], v[6:9], v[136:139], v[80:95]
	ds_read_b128 v[6:9], v239 offset:13056
	s_waitcnt lgkmcnt(3)
	v_mfma_f32_32x32x16_bf16 v[96:111], v[244:247], v[140:143], v[96:111]
	ds_read_b128 v[244:247], v239 offset:288
	s_waitcnt lgkmcnt(3)
	v_mfma_f32_32x32x16_bf16 v[80:95], v[248:251], v[140:143], v[80:95]
	ds_read_b128 v[248:251], v239 offset:13088
	s_waitcnt lgkmcnt(3)
	v_mfma_f32_32x32x16_bf16 v[96:111], v[2:5], v[144:147], v[96:111]
	ds_read_b128 v[2:5], v239 offset:320
	s_waitcnt lgkmcnt(3)
	v_mfma_f32_32x32x16_bf16 v[80:95], v[6:9], v[144:147], v[80:95]
	ds_read_b128 v[6:9], v239 offset:13120
	s_waitcnt lgkmcnt(3)
	v_mfma_f32_32x32x16_bf16 v[96:111], v[244:247], v[148:151], v[96:111]
	ds_read_b128 v[244:247], v239 offset:352
	s_waitcnt lgkmcnt(3)
	v_mfma_f32_32x32x16_bf16 v[80:95], v[248:251], v[148:151], v[80:95]
	ds_read_b128 v[248:251], v239 offset:13152
	s_waitcnt lgkmcnt(3)
	v_mfma_f32_32x32x16_bf16 v[96:111], v[2:5], v[152:155], v[96:111]
	s_waitcnt lgkmcnt(2)
	v_mfma_f32_32x32x16_bf16 v[80:95], v[6:9], v[152:155], v[80:95]
	s_waitcnt lgkmcnt(1)
	v_mfma_f32_32x32x16_bf16 v[96:111], v[244:247], v[156:159], v[96:111]
	s_waitcnt lgkmcnt(0)
	v_mfma_f32_32x32x16_bf16 v[80:95], v[248:251], v[156:159], v[80:95]
	s_nop 7
	s_nop 3
	v_max3_f32 v1, v96, s64, v97
	v_max3_f32 v1, v1, v98, v99
	v_max3_f32 v1, v1, v100, v101
	v_max3_f32 v1, v1, v102, v103
	v_max3_f32 v1, v1, v104, v105
	v_max3_f32 v1, v1, v106, v107
	v_max3_f32 v1, v1, v108, v109
	v_max3_f32 v1, v1, v110, v111
	s_nop 1
	v_max3_f32 v1, v1, v80, v81
	v_max3_f32 v1, v1, v82, v83
	v_max3_f32 v1, v1, v84, v85
	v_max3_f32 v1, v1, v86, v87
	v_max3_f32 v1, v1, v88, v89
	v_max3_f32 v1, v1, v90, v91
	v_max3_f32 v1, v1, v92, v93
	v_max3_f32 v1, v1, v94, v95
	ds_bpermute_b32 v2, v228, v1
	s_waitcnt lgkmcnt(0)
; #define MFMA(a, b, c) __builtin_amdgcn_mfma_f32_32x32x16_bf16((a), (b), (c), 0, 0, 0)
; template <int DQ, bool MASK>
; DI void attn_phase(const Params& p, unsigned char* smem, float cexp) {
;     ...
;         float mnew = fmaxf(m, mx);
;         float muse = (mnew == -INFINITY) ? 0.f : mnew;
;         float alpha = __builtin_amdgcn_exp2f((m - muse) * cexp);
;         m = mnew;
;         float ps = 0.f;
; #pragma unroll
;         for (int u = 0; u < 2; ++u)
; #pragma unroll
;           for (int i = 0; i < 16; ++i) {
;             float pv = __builtin_amdgcn_exp2f((sa[u][i] - muse) * cexp);
;             ps += pv;
;             sa[u][i] = pv;
;           }
;         l = l * alpha + ps;
; #pragma unroll
;         for (int j = 0; j < 4; ++j)
; #pragma unroll
;           for (int i = 0; i < 16; ++i) o[j][i] *= alpha;
; #pragma unroll
;         for (int u = 0; u < 2; ++u)
; #pragma unroll
;           for (int s2 = 0; s2 < 2; ++s2) {
;             uint4 pp;
;             pp.x = pack2(sa[u][8 * s2 + 0], sa[u][8 * s2 + 1]);
;             pp.y = pack2(sa[u][8 * s2 + 2], sa[u][8 * s2 + 3]);
;             pp.z = pack2(sa[u][8 * s2 + 4], sa[u][8 * s2 + 5]);
;             pp.w = pack2(sa[u][8 * s2 + 6], sa[u][8 * s2 + 7]);
;             bf16x8 pf = __builtin_bit_cast(bf16x8, pp);
; #pragma unroll
;             for (int dt = 0; dt < 4; ++dt) {
;               const bf16* vp = Vs + (32 * dt + r) * VST + 32 * u + 16 * s2 + 4 * g;
;               s16x4 lo = *(const s16x4*)vp;
;               s16x4 hi = *(const s16x4*)(vp + 8);
;               bf16x8 vf = __builtin_shufflevector(lo, hi, 0, 1, 2, 3, 4, 5, 6, 7);
;               o[dt] = MFMA(vf, pf, o[dt]);
	v_max3_f32 v1, v242, v1, v2
	v_cmp_neq_f32_e32 vcc, s64, v1
	s_nop 1
	v_cndmask_b32_e32 v3, 0, v1, vcc
	v_sub_f32_e32 v5, v100, v3
	v_mul_f32_e32 v5, 0x3dd53b94, v5
	v_exp_f32_e32 v12, v5
	v_sub_f32_e32 v5, v101, v3
	v_mul_f32_e32 v5, 0x3dd53b94, v5
	v_sub_f32_e32 v4, v96, v3
	v_exp_f32_e32 v13, v5
	v_sub_f32_e32 v5, v102, v3
	v_mul_f32_e32 v4, 0x3dd53b94, v4
	v_mul_f32_e32 v5, 0x3dd53b94, v5
	v_exp_f32_e32 v8, v4
	v_sub_f32_e32 v4, v97, v3
	v_exp_f32_e32 v14, v5
	v_sub_f32_e32 v5, v103, v3
	v_mul_f32_e32 v4, 0x3dd53b94, v4
	v_mul_f32_e32 v5, 0x3dd53b94, v5
	v_exp_f32_e32 v9, v4
	v_sub_f32_e32 v4, v98, v3
	v_exp_f32_e32 v15, v5
	v_sub_f32_e32 v5, v104, v3
	v_mul_f32_e32 v4, 0x3dd53b94, v4
	v_mul_f32_e32 v5, 0x3dd53b94, v5
	v_exp_f32_e32 v10, v4
	v_sub_f32_e32 v4, v99, v3
	v_exp_f32_e32 v96, v5
	v_sub_f32_e32 v5, v105, v3
	v_mul_f32_e32 v4, 0x3dd53b94, v4
	v_mul_f32_e32 v5, 0x3dd53b94, v5
	v_exp_f32_e32 v11, v4
	v_exp_f32_e32 v97, v5
	v_sub_f32_e32 v5, v106, v3
	v_add_f32_e32 v4, 0, v8
	v_mul_f32_e32 v5, 0x3dd53b94, v5
	v_add_f32_e32 v4, v9, v4
	v_exp_f32_e32 v98, v5
	v_sub_f32_e32 v5, v107, v3
	v_add_f32_e32 v4, v10, v4
	v_mul_f32_e32 v5, 0x3dd53b94, v5
	v_add_f32_e32 v4, v11, v4
	v_exp_f32_e32 v99, v5
	v_sub_f32_e32 v5, v108, v3
	v_add_f32_e32 v4, v12, v4
	v_mul_f32_e32 v5, 0x3dd53b94, v5
	v_add_f32_e32 v4, v13, v4
	v_exp_f32_e32 v100, v5
	v_sub_f32_e32 v5, v109, v3
	v_add_f32_e32 v4, v14, v4
	v_mul_f32_e32 v5, 0x3dd53b94, v5
	v_add_f32_e32 v4, v15, v4
	v_exp_f32_e32 v101, v5
	v_sub_f32_e32 v5, v110, v3
	v_add_f32_e32 v4, v96, v4
	v_mul_f32_e32 v5, 0x3dd53b94, v5
	v_add_f32_e32 v4, v97, v4
	v_exp_f32_e32 v102, v5
	v_sub_f32_e32 v5, v111, v3
	v_add_f32_e32 v4, v98, v4
	v_mul_f32_e32 v5, 0x3dd53b94, v5
	v_add_f32_e32 v4, v99, v4
	v_exp_f32_e32 v103, v5
	v_add_f32_e32 v4, v100, v4
	v_add_f32_e32 v4, v101, v4
	v_add_f32_e32 v4, v102, v4
	v_add_f32_e32 v104, v103, v4
	v_sub_f32_e32 v4, v80, v3
	v_mul_f32_e32 v4, 0x3dd53b94, v4
	v_exp_f32_e32 v80, v4
	v_sub_f32_e32 v4, v81, v3
	v_mul_f32_e32 v4, 0x3dd53b94, v4
	v_add_u32_e32 v105, 0x6000, v240
	v_exp_f32_e32 v81, v4
	ds_read2_b64 v[4:7], v105 offset0:128 offset1:130
	v_sub_f32_e32 v2, v242, v3
	v_mul_f32_e32 v2, 0x3dd53b94, v2
	v_exp_f32_e32 v2, v2
	v_add_u32_e32 v106, 0x7000, v240
	v_cvt_pk_bf16_f32 v8, v8, v9
	v_cvt_pk_bf16_f32 v9, v10, v11
	v_cvt_pk_bf16_f32 v10, v12, v13
	v_cvt_pk_bf16_f32 v11, v14, v15
	ds_read2_b64 v[12:15], v106 offset0:160 offset1:162
	v_pk_mul_f32 v[78:79], v[78:79], v[2:3] op_sel_hi:[1,0]
	v_pk_mul_f32 v[76:77], v[76:77], v[2:3] op_sel_hi:[1,0]
	v_pk_mul_f32 v[74:75], v[74:75], v[2:3] op_sel_hi:[1,0]
	v_pk_mul_f32 v[72:73], v[72:73], v[2:3] op_sel_hi:[1,0]
	v_pk_mul_f32 v[70:71], v[70:71], v[2:3] op_sel_hi:[1,0]
	v_pk_mul_f32 v[68:69], v[68:69], v[2:3] op_sel_hi:[1,0]
	v_pk_mul_f32 v[66:67], v[66:67], v[2:3] op_sel_hi:[1,0]
	v_pk_mul_f32 v[64:65], v[64:65], v[2:3] op_sel_hi:[1,0]
	v_add_u32_e32 v107, 0x8000, v240
	v_pk_mul_f32 v[62:63], v[62:63], v[2:3] op_sel_hi:[1,0]
	s_waitcnt lgkmcnt(1)
	v_mfma_f32_32x32x16_bf16 v[64:79], v[4:7], v[8:11], v[64:79]
	ds_read2_b64 v[4:7], v107 offset0:192 offset1:194
	v_mul_f32_e64 v60, v60, v2
	v_mul_f32_e64 v61, v61, v2
	v_mul_f32_e64 v58, v58, v2
	v_mul_f32_e64 v59, v59, v2
	v_pk_mul_f32 v[56:57], v[56:57], v[2:3] op_sel_hi:[1,0]
	v_pk_mul_f32 v[54:55], v[54:55], v[2:3] op_sel_hi:[1,0]
	v_pk_mul_f32 v[52:53], v[52:53], v[2:3] op_sel_hi:[1,0]
	v_pk_mul_f32 v[50:51], v[50:51], v[2:3] op_sel_hi:[1,0]
	v_pk_mul_f32 v[48:49], v[48:49], v[2:3] op_sel_hi:[1,0]
	v_add_u32_e32 v108, 0x9000, v240
	v_pk_mul_f32 v[46:47], v[46:47], v[2:3] op_sel_hi:[1,0]
	s_waitcnt lgkmcnt(1)
	v_mfma_f32_32x32x16_bf16 v[48:63], v[12:15], v[8:11], v[48:63]
	ds_read2_b64 v[12:15], v108 offset0:224 offset1:226
	v_mul_f32_e64 v44, v44, v2
	v_mul_f32_e64 v45, v45, v2
	v_mul_f32_e64 v42, v42, v2
	v_mul_f32_e64 v43, v43, v2
	v_pk_mul_f32 v[40:41], v[40:41], v[2:3] op_sel_hi:[1,0]
	v_pk_mul_f32 v[38:39], v[38:39], v[2:3] op_sel_hi:[1,0]
	v_pk_mul_f32 v[36:37], v[36:37], v[2:3] op_sel_hi:[1,0]
	v_pk_mul_f32 v[34:35], v[34:35], v[2:3] op_sel_hi:[1,0]
	v_pk_mul_f32 v[32:33], v[32:33], v[2:3] op_sel_hi:[1,0]
	v_pk_mul_f32 v[30:31], v[30:31], v[2:3] op_sel_hi:[1,0]
	v_pk_mul_f32 v[28:29], v[28:29], v[2:3] op_sel_hi:[1,0]
	s_waitcnt lgkmcnt(1)
; #define MFMA(a, b, c) __builtin_amdgcn_mfma_f32_32x32x16_bf16((a), (b), (c), 0, 0, 0)
; template <int DQ, bool MASK>
; DI void attn_phase(const Params& p, unsigned char* smem, float cexp) {
;     ...
; #pragma unroll
;         for (int u = 0; u < 2; ++u)
; #pragma unroll
;           for (int i = 0; i < 16; ++i) {
;             float pv = __builtin_amdgcn_exp2f((sa[u][i] - muse) * cexp);
;             ps += pv;
;             sa[u][i] = pv;
;           }
;         l = l * alpha + ps;
; #pragma unroll
;         for (int j = 0; j < 4; ++j)
; #pragma unroll
;           for (int i = 0; i < 16; ++i) o[j][i] *= alpha;
; #pragma unroll
;         for (int u = 0; u < 2; ++u)
; #pragma unroll
;           for (int s2 = 0; s2 < 2; ++s2) {
;             uint4 pp;
;             pp.x = pack2(sa[u][8 * s2 + 0], sa[u][8 * s2 + 1]);
;             pp.y = pack2(sa[u][8 * s2 + 2], sa[u][8 * s2 + 3]);
;             pp.z = pack2(sa[u][8 * s2 + 4], sa[u][8 * s2 + 5]);
;             pp.w = pack2(sa[u][8 * s2 + 6], sa[u][8 * s2 + 7]);
;             bf16x8 pf = __builtin_bit_cast(bf16x8, pp);
; #pragma unroll
;             for (int dt = 0; dt < 4; ++dt) {
;               const bf16* vp = Vs + (32 * dt + r) * VST + 32 * u + 16 * s2 + 4 * g;
;               s16x4 lo = *(const s16x4*)vp;
;               s16x4 hi = *(const s16x4*)(vp + 8);
;               bf16x8 vf = __builtin_shufflevector(lo, hi, 0, 1, 2, 3, 4, 5, 6, 7);
;               o[dt] = MFMA(vf, pf, o[dt]);
;             }
;           }
;       }
	v_mfma_f32_32x32x16_bf16 v[32:47], v[4:7], v[8:11], v[32:47]
	ds_read2_b64 v[4:7], v105 offset0:132 offset1:134
	v_mul_f32_e64 v26, v26, v2
	v_mul_f32_e64 v27, v27, v2
	v_mul_f32_e64 v24, v24, v2
	v_mul_f32_e64 v25, v25, v2
	v_pk_mul_f32 v[22:23], v[22:23], v[2:3] op_sel_hi:[1,0]
	v_pk_mul_f32 v[20:21], v[20:21], v[2:3] op_sel_hi:[1,0]
	v_pk_mul_f32 v[18:19], v[18:19], v[2:3] op_sel_hi:[1,0]
	v_pk_mul_f32 v[16:17], v[16:17], v[2:3] op_sel_hi:[1,0]
	v_sub_f32_e32 v89, v89, v3
	v_sub_f32_e32 v91, v91, v3
	s_waitcnt lgkmcnt(1)
	v_mfma_f32_32x32x16_bf16 v[16:31], v[12:15], v[8:11], v[16:31]
	v_sub_f32_e32 v8, v82, v3
	v_mul_f32_e32 v82, 0x3dd53b94, v8
	v_cvt_pk_bf16_f32 v8, v96, v97
	v_cvt_pk_bf16_f32 v9, v98, v99
	v_cvt_pk_bf16_f32 v10, v100, v101
	v_cvt_pk_bf16_f32 v11, v102, v103
	ds_read2_b64 v[12:15], v106 offset0:164 offset1:166
	v_exp_f32_e32 v82, v82
	s_waitcnt lgkmcnt(1)
	v_mfma_f32_32x32x16_bf16 v[64:79], v[4:7], v[8:11], v[64:79]
	v_sub_f32_e32 v4, v83, v3
	v_mul_f32_e32 v4, 0x3dd53b94, v4
	v_exp_f32_e32 v83, v4
	v_sub_f32_e32 v4, v84, v3
	v_mul_f32_e32 v84, 0x3dd53b94, v4
	ds_read2_b64 v[4:7], v107 offset0:196 offset1:198
	v_exp_f32_e32 v84, v84
	s_waitcnt lgkmcnt(1)
	v_mfma_f32_32x32x16_bf16 v[48:63], v[12:15], v[8:11], v[48:63]
	v_sub_f32_e32 v12, v85, v3
	v_mul_f32_e32 v12, 0x3dd53b94, v12
	v_exp_f32_e32 v85, v12
	v_sub_f32_e32 v12, v86, v3
	v_mul_f32_e32 v86, 0x3dd53b94, v12
	ds_read2_b64 v[12:15], v108 offset0:228 offset1:230
	v_exp_f32_e32 v86, v86
	s_waitcnt lgkmcnt(1)
	v_mfma_f32_32x32x16_bf16 v[32:47], v[4:7], v[8:11], v[32:47]
	v_sub_f32_e32 v4, v87, v3
	v_mul_f32_e32 v4, 0x3dd53b94, v4
	v_exp_f32_e32 v87, v4
	v_sub_f32_e32 v4, v88, v3
	v_mul_f32_e32 v88, 0x3dd53b94, v4
	ds_read2_b64 v[4:7], v105 offset0:136 offset1:138
	v_sub_f32_e32 v93, v93, v3
	s_waitcnt lgkmcnt(1)
	v_mfma_f32_32x32x16_bf16 v[16:31], v[12:15], v[8:11], v[16:31]
	v_cvt_pk_bf16_f32 v8, v80, v81
	v_cvt_pk_bf16_f32 v9, v82, v83
	v_cvt_pk_bf16_f32 v10, v84, v85
	v_cvt_pk_bf16_f32 v11, v86, v87
	ds_read2_b64 v[12:15], v106 offset0:168 offset1:170
	v_exp_f32_e32 v88, v88
	v_mov_b32_e32 v242, v1
	s_waitcnt lgkmcnt(1)
	v_mfma_f32_32x32x16_bf16 v[64:79], v[4:7], v[8:11], v[64:79]
	v_mul_f32_e32 v4, 0x3dd53b94, v89
	v_exp_f32_e32 v89, v4
	v_sub_f32_e32 v4, v90, v3
	v_mul_f32_e32 v4, 0x3dd53b94, v4
	v_exp_f32_e32 v90, v4
	ds_read2_b64 v[4:7], v107 offset0:200 offset1:202
	s_waitcnt lgkmcnt(1)
	v_mfma_f32_32x32x16_bf16 v[48:63], v[12:15], v[8:11], v[48:63]
	v_mul_f32_e32 v12, 0x3dd53b94, v91
	v_exp_f32_e32 v91, v12
	v_sub_f32_e32 v12, v92, v3
	v_mul_f32_e32 v12, 0x3dd53b94, v12
	v_exp_f32_e32 v92, v12
	ds_read2_b64 v[12:15], v108 offset0:232 offset1:234
	s_waitcnt lgkmcnt(1)
	v_mfma_f32_32x32x16_bf16 v[32:47], v[4:7], v[8:11], v[32:47]
	v_mul_f32_e32 v4, 0x3dd53b94, v93
	v_exp_f32_e32 v93, v4
	v_sub_f32_e32 v4, v94, v3
	v_mul_f32_e32 v4, 0x3dd53b94, v4
	v_exp_f32_e32 v94, v4
	ds_read2_b64 v[4:7], v105 offset0:140 offset1:142
	v_sub_f32_e32 v3, v95, v3
	v_mul_f32_e32 v3, 0x3dd53b94, v3
	v_exp_f32_e32 v3, v3
	s_waitcnt lgkmcnt(1)
	v_mfma_f32_32x32x16_bf16 v[16:31], v[12:15], v[8:11], v[16:31]
	ds_read2_b64 v[12:15], v106 offset0:172 offset1:174
	v_cvt_pk_bf16_f32 v8, v88, v89
	v_cvt_pk_bf16_f32 v9, v90, v91
	v_cvt_pk_bf16_f32 v10, v92, v93
	v_cvt_pk_bf16_f32 v11, v94, v3
	s_waitcnt lgkmcnt(1)
	s_nop 0
	v_mfma_f32_32x32x16_bf16 v[64:79], v[4:7], v[8:11], v[64:79]
	v_add_f32_e32 v4, v80, v104
	v_add_f32_e32 v4, v81, v4
	v_add_f32_e32 v4, v82, v4
	v_add_f32_e32 v4, v83, v4
	v_add_f32_e32 v4, v84, v4
	v_add_f32_e32 v80, v85, v4
	ds_read2_b64 v[4:7], v107 offset0:204 offset1:206
	s_waitcnt lgkmcnt(1)
	v_mfma_f32_32x32x16_bf16 v[48:63], v[12:15], v[8:11], v[48:63]
	v_add_f32_e32 v12, v86, v80
	v_add_f32_e32 v12, v87, v12
	v_add_f32_e32 v12, v88, v12
	v_add_f32_e32 v12, v89, v12
	v_add_f32_e32 v12, v90, v12
	v_add_f32_e32 v80, v91, v12
	ds_read2_b64 v[12:15], v108 offset0:236 offset1:238
	s_waitcnt lgkmcnt(1)
	v_mfma_f32_32x32x16_bf16 v[32:47], v[4:7], v[8:11], v[32:47]
	v_add_f32_e32 v4, v92, v80
	v_add_f32_e32 v4, v93, v4
	v_add_f32_e32 v4, v94, v4
	v_add_f32_e32 v3, v3, v4
	v_fmac_f32_e32 v3, v241, v2
	v_mov_b32_e32 v241, v3
	s_waitcnt lgkmcnt(0)
	v_mfma_f32_32x32x16_bf16 v[16:31], v[12:15], v[8:11], v[16:31]
	s_branch .LBB0_421
